# v13: v9 + layer-0 in-proj phase weight conversion (out+up, blocks 192-255) rewritten as 3-deep pipelined passes with 2 LDS buffers
# baseline (speedup 1.0000x reference)
.LBB0_559:
	s_and_b32 s2, s30, 0xffffffc0
	s_cmpk_lg_i32 s2, 0xc0
	s_cbranch_scc1 .LBB0_587
	v_mov_b32_e32 v1, 0
	ds_read_b64 v[2:3], v1 offset:416
	ds_read_b64 v[4:5], v1 offset:176
	ds_read_b64 v[6:7], v1 offset:184
	s_waitcnt lgkmcnt(0)
	v_readfirstlane_b32 s14, v2
	v_readfirstlane_b32 s15, v3
	v_readfirstlane_b32 s6, v4
	v_readfirstlane_b32 s7, v5
	v_readfirstlane_b32 s8, v6
	v_readfirstlane_b32 s9, v7
	v_lshrrev_b32_e32 v163, 4, v0
	v_and_b32_e32 v164, 15, v0
	v_lshlrev_b32_e32 v164, 4, v164
	v_mul_u32_u24_e32 v146, 0x104, v163
	v_add_u32_e32 v146, v146, v164
	v_add_u32_e32 v146, 0x400, v146
	v_lshrrev_b32_e32 v165, 3, v0
	v_and_b32_e32 v166, 7, v0
	v_lshlrev_b32_e32 v166, 3, v166
	v_mul_u32_u24_e32 v147, 0x104, v166
	v_lshlrev_b32_e32 v167, 2, v165
	v_add_u32_e32 v147, v147, v167
	v_add_u32_e32 v147, 0x400, v147
	v_lshl_add_u32 v157, v163, 12, v164
	v_add_u32_e32 v158, 0x20000, v157
	v_mul_u32_u24_e32 v159, 0x5800, v163
	v_add_u32_e32 v159, v159, v164
	v_add_u32_e32 v160, 0xb0000, v159
	v_lshlrev_b32_e32 v167, 1, v166
	v_lshl_add_u32 v161, v165, 11, v167
	v_mul_u32_u24_e32 v162, 0x1600, v165
	v_add_u32_e32 v162, v162, v167
	s_add_u32 s10, s14, 0x4c8000
	s_addc_u32 s11, s15, 0
	s_add_u32 s12, s14, 0x8c8000
	s_addc_u32 s13, s15, 0
	s_add_i32 s4, s30, 0xffffff40
	s_add_i32 s16, s4, 0
	s_and_b32 s17, s16, 15
	s_lshr_b32 s18, s16, 4
	s_mul_i32 s17, s17, 262144
	s_lshl_b32 s18, s18, 8
	s_add_u32 s17, s17, s18
	s_add_u32 s20, s6, s17
	s_addc_u32 s21, s7, 0
	global_load_dwordx4 v[2:5], v157, s[20:21]
	global_load_dwordx4 v[6:9], v158, s[20:21]
	s_add_i32 s16, s4, 64
	s_and_b32 s17, s16, 15
	s_lshr_b32 s18, s16, 4
	s_mul_i32 s17, s17, 262144
	s_lshl_b32 s18, s18, 8
	s_add_u32 s17, s17, s18
	s_add_u32 s20, s6, s17
	s_addc_u32 s21, s7, 0
	global_load_dwordx4 v[10:13], v157, s[20:21]
	global_load_dwordx4 v[14:17], v158, s[20:21]
	s_add_i32 s16, s4, 128
	s_and_b32 s17, s16, 15
	s_lshr_b32 s18, s16, 4
	s_mul_i32 s17, s17, 262144
	s_lshl_b32 s18, s18, 8
	s_add_u32 s17, s17, s18
	s_add_u32 s20, s6, s17
	s_addc_u32 s21, s7, 0
	global_load_dwordx4 v[18:21], v157, s[20:21]
	global_load_dwordx4 v[22:25], v158, s[20:21]
	s_add_i32 s16, s4, 192
	s_and_b32 s17, s16, 15
	s_lshr_b32 s18, s16, 4
	s_mul_i32 s17, s17, 262144
	s_lshl_b32 s18, s18, 8
	s_add_u32 s17, s17, s18
	s_add_u32 s20, s6, s17
	s_addc_u32 s21, s7, 0
	global_load_dwordx4 v[26:29], v157, s[20:21]
	global_load_dwordx4 v[30:33], v158, s[20:21]
	s_add_i32 s16, s4, 0
	s_and_b32 s17, s16, 15
	s_lshr_b32 s18, s16, 4
	s_mul_i32 s17, s17, 1441792
	s_lshl_b32 s18, s18, 8
	s_add_u32 s17, s17, s18
	s_add_u32 s20, s8, s17
	s_addc_u32 s21, s9, 0
	global_load_dwordx4 v[34:37], v159, s[20:21]
	global_load_dwordx4 v[38:41], v160, s[20:21]
	s_add_i32 s16, s4, 64
	s_and_b32 s17, s16, 15
	s_lshr_b32 s18, s16, 4
	s_mul_i32 s17, s17, 1441792
	s_lshl_b32 s18, s18, 8
	s_add_u32 s17, s17, s18
	s_add_u32 s20, s8, s17
	s_addc_u32 s21, s9, 0
	global_load_dwordx4 v[42:45], v159, s[20:21]
	global_load_dwordx4 v[46:49], v160, s[20:21]
	s_add_i32 s16, s4, 128
	s_and_b32 s17, s16, 15
	s_lshr_b32 s18, s16, 4
	s_mul_i32 s17, s17, 1441792
	s_lshl_b32 s18, s18, 8
	s_add_u32 s17, s17, s18
	s_add_u32 s20, s8, s17
	s_addc_u32 s21, s9, 0
	global_load_dwordx4 v[50:53], v159, s[20:21]
	global_load_dwordx4 v[54:57], v160, s[20:21]
	s_add_i32 s16, s4, 192
	s_and_b32 s17, s16, 15
	s_lshr_b32 s18, s16, 4
	s_mul_i32 s17, s17, 1441792
	s_lshl_b32 s18, s18, 8
	s_add_u32 s17, s17, s18
	s_add_u32 s20, s8, s17
	s_addc_u32 s21, s9, 0
	global_load_dwordx4 v[58:61], v159, s[20:21]
	global_load_dwordx4 v[62:65], v160, s[20:21]
	s_add_i32 s16, s4, 256
	s_and_b32 s17, s16, 15
	s_lshr_b32 s18, s16, 4
	s_mul_i32 s17, s17, 1441792
	s_lshl_b32 s18, s18, 8
	s_add_u32 s17, s17, s18
	s_add_u32 s20, s8, s17
	s_addc_u32 s21, s9, 0
	global_load_dwordx4 v[66:69], v159, s[20:21]
	global_load_dwordx4 v[70:73], v160, s[20:21]
	s_add_i32 s16, s4, 320
	s_and_b32 s17, s16, 15
	s_lshr_b32 s18, s16, 4
	s_mul_i32 s17, s17, 1441792
	s_lshl_b32 s18, s18, 8
	s_add_u32 s17, s17, s18
	s_add_u32 s20, s8, s17
	s_addc_u32 s21, s9, 0
	global_load_dwordx4 v[74:77], v159, s[20:21]
	global_load_dwordx4 v[78:81], v160, s[20:21]
	s_add_i32 s16, s4, 384
	s_and_b32 s17, s16, 15
	s_lshr_b32 s18, s16, 4
	s_mul_i32 s17, s17, 1441792
	s_lshl_b32 s18, s18, 8
	s_add_u32 s17, s17, s18
	s_add_u32 s20, s8, s17
	s_addc_u32 s21, s9, 0
	global_load_dwordx4 v[82:85], v159, s[20:21]
	global_load_dwordx4 v[86:89], v160, s[20:21]
	s_add_i32 s16, s4, 448
	s_and_b32 s17, s16, 15
	s_lshr_b32 s18, s16, 4
	s_mul_i32 s17, s17, 1441792
	s_lshl_b32 s18, s18, 8
	s_add_u32 s17, s17, s18
	s_add_u32 s20, s8, s17
	s_addc_u32 s21, s9, 0
	global_load_dwordx4 v[90:93], v159, s[20:21]
	global_load_dwordx4 v[94:97], v160, s[20:21]
	s_waitcnt vmcnt(16)
	v_add_u32_e32 v148, 0x0, v146
	ds_write2_b32 v148, v2, v3 offset1:1
	ds_write2_b32 v148, v4, v5 offset0:2 offset1:3
	v_add_u32_e32 v148, 0x2080, v146
	ds_write2_b32 v148, v6, v7 offset1:1
	ds_write2_b32 v148, v8, v9 offset0:2 offset1:3
	v_add_u32_e32 v148, 0x4100, v146
	ds_write2_b32 v148, v10, v11 offset1:1
	ds_write2_b32 v148, v12, v13 offset0:2 offset1:3
	v_add_u32_e32 v148, 0x6180, v146
	ds_write2_b32 v148, v14, v15 offset1:1
	ds_write2_b32 v148, v16, v17 offset0:2 offset1:3
	v_add_u32_e32 v148, 0x8200, v146
	ds_write2_b32 v148, v18, v19 offset1:1
	ds_write2_b32 v148, v20, v21 offset0:2 offset1:3
	v_add_u32_e32 v148, 0xa280, v146
	ds_write2_b32 v148, v22, v23 offset1:1
	ds_write2_b32 v148, v24, v25 offset0:2 offset1:3
	v_add_u32_e32 v148, 0xc300, v146
	ds_write2_b32 v148, v26, v27 offset1:1
	ds_write2_b32 v148, v28, v29 offset0:2 offset1:3
	v_add_u32_e32 v148, 0xe380, v146
	ds_write2_b32 v148, v30, v31 offset1:1
	ds_write2_b32 v148, v32, v33 offset0:2 offset1:3
	s_waitcnt lgkmcnt(0)
	s_add_i32 s16, s4, 512
	s_and_b32 s17, s16, 15
	s_lshr_b32 s18, s16, 4
	s_mul_i32 s17, s17, 1441792
	s_lshl_b32 s18, s18, 8
	s_add_u32 s17, s17, s18
	s_add_u32 s20, s8, s17
	s_addc_u32 s21, s9, 0
	global_load_dwordx4 v[2:5], v159, s[20:21]
	global_load_dwordx4 v[6:9], v160, s[20:21]
	s_add_i32 s16, s4, 576
	s_and_b32 s17, s16, 15
	s_lshr_b32 s18, s16, 4
	s_mul_i32 s17, s17, 1441792
	s_lshl_b32 s18, s18, 8
	s_add_u32 s17, s17, s18
	s_add_u32 s20, s8, s17
	s_addc_u32 s21, s9, 0
	global_load_dwordx4 v[10:13], v159, s[20:21]
	global_load_dwordx4 v[14:17], v160, s[20:21]
	s_add_i32 s16, s4, 640
	s_and_b32 s17, s16, 15
	s_lshr_b32 s18, s16, 4
	s_mul_i32 s17, s17, 1441792
	s_lshl_b32 s18, s18, 8
	s_add_u32 s17, s17, s18
	s_add_u32 s20, s8, s17
	s_addc_u32 s21, s9, 0
	global_load_dwordx4 v[18:21], v159, s[20:21]
	global_load_dwordx4 v[22:25], v160, s[20:21]
	s_add_i32 s16, s4, 704
	s_and_b32 s17, s16, 15
	s_lshr_b32 s18, s16, 4
	s_mul_i32 s17, s17, 1441792
	s_lshl_b32 s18, s18, 8
	s_add_u32 s17, s17, s18
	s_add_u32 s20, s8, s17
	s_addc_u32 s21, s9, 0
	global_load_dwordx4 v[26:29], v159, s[20:21]
	global_load_dwordx4 v[30:33], v160, s[20:21]
	s_barrier
	v_add_u32_e32 v149, 0x0, v147
	v_add_u32_e32 v150, 0x400, v147
	ds_read2_b32 v[98:99], v149 offset1:65
	ds_read2_b32 v[100:101], v149 offset0:130 offset1:195
	ds_read2_b32 v[102:103], v150 offset0:4 offset1:69
	ds_read2_b32 v[104:105], v150 offset0:134 offset1:199
	v_add_u32_e32 v151, 0x4100, v147
	v_add_u32_e32 v152, 0x4500, v147
	ds_read2_b32 v[106:107], v151 offset1:65
	ds_read2_b32 v[108:109], v151 offset0:130 offset1:195
	ds_read2_b32 v[110:111], v152 offset0:4 offset1:69
	ds_read2_b32 v[112:113], v152 offset0:134 offset1:199
	v_add_u32_e32 v153, 0x8200, v147
	v_add_u32_e32 v154, 0x8600, v147
	ds_read2_b32 v[114:115], v153 offset1:65
	ds_read2_b32 v[116:117], v153 offset0:130 offset1:195
	ds_read2_b32 v[118:119], v154 offset0:4 offset1:69
	ds_read2_b32 v[120:121], v154 offset0:134 offset1:199
	v_add_u32_e32 v155, 0xc300, v147
	v_add_u32_e32 v156, 0xc700, v147
	ds_read2_b32 v[122:123], v155 offset1:65
	ds_read2_b32 v[124:125], v155 offset0:130 offset1:195
	ds_read2_b32 v[126:127], v156 offset0:4 offset1:69
	ds_read2_b32 v[128:129], v156 offset0:134 offset1:199
	s_add_i32 s16, s4, 0
	s_and_b32 s17, s16, 15
	s_lshr_b32 s18, s16, 4
	s_lshl_b32 s22, s18, 6
	s_mul_i32 s22, s22, 2048
	s_lshl_b32 s17, s17, 7
	s_add_u32 s22, s22, s17
	s_add_u32 s20, s10, s22
	s_addc_u32 s21, s11, 0
	s_waitcnt lgkmcnt(12)
	v_cvt_pk_bf16_f32 v130, v98, v99
	v_cvt_pk_bf16_f32 v131, v100, v101
	v_cvt_pk_bf16_f32 v132, v102, v103
	v_cvt_pk_bf16_f32 v133, v104, v105
	global_store_dwordx4 v161, v[130:133], s[20:21] sc1
	s_add_i32 s16, s4, 64
	s_and_b32 s17, s16, 15
	s_lshr_b32 s18, s16, 4
	s_lshl_b32 s22, s18, 6
	s_mul_i32 s22, s22, 2048
	s_lshl_b32 s17, s17, 7
	s_add_u32 s22, s22, s17
	s_add_u32 s20, s10, s22
	s_addc_u32 s21, s11, 0
	s_waitcnt lgkmcnt(8)
	v_cvt_pk_bf16_f32 v134, v106, v107
	v_cvt_pk_bf16_f32 v135, v108, v109
	v_cvt_pk_bf16_f32 v136, v110, v111
	v_cvt_pk_bf16_f32 v137, v112, v113
	global_store_dwordx4 v161, v[134:137], s[20:21] sc1
	s_add_i32 s16, s4, 128
	s_and_b32 s17, s16, 15
	s_lshr_b32 s18, s16, 4
	s_lshl_b32 s22, s18, 6
	s_mul_i32 s22, s22, 2048
	s_lshl_b32 s17, s17, 7
	s_add_u32 s22, s22, s17
	s_add_u32 s20, s10, s22
	s_addc_u32 s21, s11, 0
	s_waitcnt lgkmcnt(4)
	v_cvt_pk_bf16_f32 v138, v114, v115
	v_cvt_pk_bf16_f32 v139, v116, v117
	v_cvt_pk_bf16_f32 v140, v118, v119
	v_cvt_pk_bf16_f32 v141, v120, v121
	global_store_dwordx4 v161, v[138:141], s[20:21] sc1
	s_add_i32 s16, s4, 192
	s_and_b32 s17, s16, 15
	s_lshr_b32 s18, s16, 4
	s_lshl_b32 s22, s18, 6
	s_mul_i32 s22, s22, 2048
	s_lshl_b32 s17, s17, 7
	s_add_u32 s22, s22, s17
	s_add_u32 s20, s10, s22
	s_addc_u32 s21, s11, 0
	s_waitcnt lgkmcnt(0)
	v_cvt_pk_bf16_f32 v142, v122, v123
	v_cvt_pk_bf16_f32 v143, v124, v125
	v_cvt_pk_bf16_f32 v144, v126, v127
	v_cvt_pk_bf16_f32 v145, v128, v129
	global_store_dwordx4 v161, v[142:145], s[20:21] sc1
	s_waitcnt vmcnt(20)
	v_add_u32_e32 v148, 0x10400, v146
	ds_write2_b32 v148, v34, v35 offset1:1
	ds_write2_b32 v148, v36, v37 offset0:2 offset1:3
	v_add_u32_e32 v148, 0x12480, v146
	ds_write2_b32 v148, v38, v39 offset1:1
	ds_write2_b32 v148, v40, v41 offset0:2 offset1:3
	v_add_u32_e32 v148, 0x14500, v146
	ds_write2_b32 v148, v42, v43 offset1:1
	ds_write2_b32 v148, v44, v45 offset0:2 offset1:3
	v_add_u32_e32 v148, 0x16580, v146
	ds_write2_b32 v148, v46, v47 offset1:1
	ds_write2_b32 v148, v48, v49 offset0:2 offset1:3
	v_add_u32_e32 v148, 0x18600, v146
	ds_write2_b32 v148, v50, v51 offset1:1
	ds_write2_b32 v148, v52, v53 offset0:2 offset1:3
	v_add_u32_e32 v148, 0x1a680, v146
	ds_write2_b32 v148, v54, v55 offset1:1
	ds_write2_b32 v148, v56, v57 offset0:2 offset1:3
	v_add_u32_e32 v148, 0x1c700, v146
	ds_write2_b32 v148, v58, v59 offset1:1
	ds_write2_b32 v148, v60, v61 offset0:2 offset1:3
	v_add_u32_e32 v148, 0x1e780, v146
	ds_write2_b32 v148, v62, v63 offset1:1
	ds_write2_b32 v148, v64, v65 offset0:2 offset1:3
	s_waitcnt lgkmcnt(0)
	s_add_i32 s16, s4, 768
	s_and_b32 s17, s16, 15
	s_lshr_b32 s18, s16, 4
	s_mul_i32 s17, s17, 1441792
	s_lshl_b32 s18, s18, 8
	s_add_u32 s17, s17, s18
	s_add_u32 s20, s8, s17
	s_addc_u32 s21, s9, 0
	global_load_dwordx4 v[34:37], v159, s[20:21]
	global_load_dwordx4 v[38:41], v160, s[20:21]
	s_add_i32 s16, s4, 832
	s_and_b32 s17, s16, 15
	s_lshr_b32 s18, s16, 4
	s_mul_i32 s17, s17, 1441792
	s_lshl_b32 s18, s18, 8
	s_add_u32 s17, s17, s18
	s_add_u32 s20, s8, s17
	s_addc_u32 s21, s9, 0
	global_load_dwordx4 v[42:45], v159, s[20:21]
	global_load_dwordx4 v[46:49], v160, s[20:21]
	s_add_i32 s16, s4, 896
	s_and_b32 s17, s16, 15
	s_lshr_b32 s18, s16, 4
	s_mul_i32 s17, s17, 1441792
	s_lshl_b32 s18, s18, 8
	s_add_u32 s17, s17, s18
	s_add_u32 s20, s8, s17
	s_addc_u32 s21, s9, 0
	global_load_dwordx4 v[50:53], v159, s[20:21]
	global_load_dwordx4 v[54:57], v160, s[20:21]
	s_add_i32 s16, s4, 960
	s_and_b32 s17, s16, 15
	s_lshr_b32 s18, s16, 4
	s_mul_i32 s17, s17, 1441792
	s_lshl_b32 s18, s18, 8
	s_add_u32 s17, s17, s18
	s_add_u32 s20, s8, s17
	s_addc_u32 s21, s9, 0
	global_load_dwordx4 v[58:61], v159, s[20:21]
	global_load_dwordx4 v[62:65], v160, s[20:21]
	s_barrier
	v_add_u32_e32 v149, 0x10400, v147
	v_add_u32_e32 v150, 0x10800, v147
	ds_read2_b32 v[98:99], v149 offset1:65
	ds_read2_b32 v[100:101], v149 offset0:130 offset1:195
	ds_read2_b32 v[102:103], v150 offset0:4 offset1:69
	ds_read2_b32 v[104:105], v150 offset0:134 offset1:199
	v_add_u32_e32 v151, 0x14500, v147
	v_add_u32_e32 v152, 0x14900, v147
	ds_read2_b32 v[106:107], v151 offset1:65
	ds_read2_b32 v[108:109], v151 offset0:130 offset1:195
	ds_read2_b32 v[110:111], v152 offset0:4 offset1:69
	ds_read2_b32 v[112:113], v152 offset0:134 offset1:199
	v_add_u32_e32 v153, 0x18600, v147
	v_add_u32_e32 v154, 0x18a00, v147
	ds_read2_b32 v[114:115], v153 offset1:65
	ds_read2_b32 v[116:117], v153 offset0:130 offset1:195
	ds_read2_b32 v[118:119], v154 offset0:4 offset1:69
	ds_read2_b32 v[120:121], v154 offset0:134 offset1:199
	v_add_u32_e32 v155, 0x1c700, v147
	v_add_u32_e32 v156, 0x1cb00, v147
	ds_read2_b32 v[122:123], v155 offset1:65
	ds_read2_b32 v[124:125], v155 offset0:130 offset1:195
	ds_read2_b32 v[126:127], v156 offset0:4 offset1:69
	ds_read2_b32 v[128:129], v156 offset0:134 offset1:199
	s_add_i32 s16, s4, 0
	s_and_b32 s17, s16, 15
	s_lshr_b32 s18, s16, 4
	s_sub_i32 s23, s18, 44
	s_cmp_lt_u32 s18, 44
	s_cselect_b32 s22, s18, s23
	s_cselect_b32 s23, 0, 0x80
	s_lshr_b32 s18, s22, 1
	s_lshl_b32 s18, s18, 8
	s_and_b32 s22, s22, 1
	s_lshl_b32 s22, s22, 6
	s_add_i32 s22, s22, s18
	s_add_i32 s22, s22, s23
	s_mul_i32 s22, s22, 2048
	s_lshl_b32 s17, s17, 7
	s_add_u32 s22, s22, s17
	s_add_u32 s20, s12, s22
	s_addc_u32 s21, s13, 0
	s_waitcnt lgkmcnt(12)
	v_cvt_pk_bf16_f32 v130, v98, v99
	v_cvt_pk_bf16_f32 v131, v100, v101
	v_cvt_pk_bf16_f32 v132, v102, v103
	v_cvt_pk_bf16_f32 v133, v104, v105
	global_store_dwordx4 v161, v[130:133], s[20:21] sc1
	s_add_i32 s16, s4, 64
	s_and_b32 s17, s16, 15
	s_lshr_b32 s18, s16, 4
	s_sub_i32 s23, s18, 44
	s_cmp_lt_u32 s18, 44
	s_cselect_b32 s22, s18, s23
	s_cselect_b32 s23, 0, 0x80
	s_lshr_b32 s18, s22, 1
	s_lshl_b32 s18, s18, 8
	s_and_b32 s22, s22, 1
	s_lshl_b32 s22, s22, 6
	s_add_i32 s22, s22, s18
	s_add_i32 s22, s22, s23
	s_mul_i32 s22, s22, 2048
	s_lshl_b32 s17, s17, 7
	s_add_u32 s22, s22, s17
	s_add_u32 s20, s12, s22
	s_addc_u32 s21, s13, 0
	s_waitcnt lgkmcnt(8)
	v_cvt_pk_bf16_f32 v134, v106, v107
	v_cvt_pk_bf16_f32 v135, v108, v109
	v_cvt_pk_bf16_f32 v136, v110, v111
	v_cvt_pk_bf16_f32 v137, v112, v113
	global_store_dwordx4 v161, v[134:137], s[20:21] sc1
	s_add_i32 s16, s4, 128
	s_and_b32 s17, s16, 15
	s_lshr_b32 s18, s16, 4
	s_sub_i32 s23, s18, 44
	s_cmp_lt_u32 s18, 44
	s_cselect_b32 s22, s18, s23
	s_cselect_b32 s23, 0, 0x80
	s_lshr_b32 s18, s22, 1
	s_lshl_b32 s18, s18, 8
	s_and_b32 s22, s22, 1
	s_lshl_b32 s22, s22, 6
	s_add_i32 s22, s22, s18
	s_add_i32 s22, s22, s23
	s_mul_i32 s22, s22, 2048
	s_lshl_b32 s17, s17, 7
	s_add_u32 s22, s22, s17
	s_add_u32 s20, s12, s22
	s_addc_u32 s21, s13, 0
	s_waitcnt lgkmcnt(4)
	v_cvt_pk_bf16_f32 v138, v114, v115
	v_cvt_pk_bf16_f32 v139, v116, v117
	v_cvt_pk_bf16_f32 v140, v118, v119
	v_cvt_pk_bf16_f32 v141, v120, v121
	global_store_dwordx4 v161, v[138:141], s[20:21] sc1
	s_add_i32 s16, s4, 192
	s_and_b32 s17, s16, 15
	s_lshr_b32 s18, s16, 4
	s_sub_i32 s23, s18, 44
	s_cmp_lt_u32 s18, 44
	s_cselect_b32 s22, s18, s23
	s_cselect_b32 s23, 0, 0x80
	s_lshr_b32 s18, s22, 1
	s_lshl_b32 s18, s18, 8
	s_and_b32 s22, s22, 1
	s_lshl_b32 s22, s22, 6
	s_add_i32 s22, s22, s18
	s_add_i32 s22, s22, s23
	s_mul_i32 s22, s22, 2048
	s_lshl_b32 s17, s17, 7
	s_add_u32 s22, s22, s17
	s_add_u32 s20, s12, s22
	s_addc_u32 s21, s13, 0
	s_waitcnt lgkmcnt(0)
	v_cvt_pk_bf16_f32 v142, v122, v123
	v_cvt_pk_bf16_f32 v143, v124, v125
	v_cvt_pk_bf16_f32 v144, v126, v127
	v_cvt_pk_bf16_f32 v145, v128, v129
	global_store_dwordx4 v161, v[142:145], s[20:21] sc1
	s_waitcnt vmcnt(24)
	v_add_u32_e32 v148, 0x0, v146
	ds_write2_b32 v148, v66, v67 offset1:1
	ds_write2_b32 v148, v68, v69 offset0:2 offset1:3
	v_add_u32_e32 v148, 0x2080, v146
	ds_write2_b32 v148, v70, v71 offset1:1
	ds_write2_b32 v148, v72, v73 offset0:2 offset1:3
	v_add_u32_e32 v148, 0x4100, v146
	ds_write2_b32 v148, v74, v75 offset1:1
	ds_write2_b32 v148, v76, v77 offset0:2 offset1:3
	v_add_u32_e32 v148, 0x6180, v146
	ds_write2_b32 v148, v78, v79 offset1:1
	ds_write2_b32 v148, v80, v81 offset0:2 offset1:3
	v_add_u32_e32 v148, 0x8200, v146
	ds_write2_b32 v148, v82, v83 offset1:1
	ds_write2_b32 v148, v84, v85 offset0:2 offset1:3
	v_add_u32_e32 v148, 0xa280, v146
	ds_write2_b32 v148, v86, v87 offset1:1
	ds_write2_b32 v148, v88, v89 offset0:2 offset1:3
	v_add_u32_e32 v148, 0xc300, v146
	ds_write2_b32 v148, v90, v91 offset1:1
	ds_write2_b32 v148, v92, v93 offset0:2 offset1:3
	v_add_u32_e32 v148, 0xe380, v146
	ds_write2_b32 v148, v94, v95 offset1:1
	ds_write2_b32 v148, v96, v97 offset0:2 offset1:3
	s_waitcnt lgkmcnt(0)
	s_add_i32 s16, s4, 1024
	s_and_b32 s17, s16, 15
	s_lshr_b32 s18, s16, 4
	s_mul_i32 s17, s17, 1441792
	s_lshl_b32 s18, s18, 8
	s_add_u32 s17, s17, s18
	s_add_u32 s20, s8, s17
	s_addc_u32 s21, s9, 0
	global_load_dwordx4 v[66:69], v159, s[20:21]
	global_load_dwordx4 v[70:73], v160, s[20:21]
	s_add_i32 s16, s4, 1088
	s_and_b32 s17, s16, 15
	s_lshr_b32 s18, s16, 4
	s_mul_i32 s17, s17, 1441792
	s_lshl_b32 s18, s18, 8
	s_add_u32 s17, s17, s18
	s_add_u32 s20, s8, s17
	s_addc_u32 s21, s9, 0
	global_load_dwordx4 v[74:77], v159, s[20:21]
	global_load_dwordx4 v[78:81], v160, s[20:21]
	s_add_i32 s16, s4, 1152
	s_and_b32 s17, s16, 15
	s_lshr_b32 s18, s16, 4
	s_mul_i32 s17, s17, 1441792
	s_lshl_b32 s18, s18, 8
	s_add_u32 s17, s17, s18
	s_add_u32 s20, s8, s17
	s_addc_u32 s21, s9, 0
	global_load_dwordx4 v[82:85], v159, s[20:21]
	global_load_dwordx4 v[86:89], v160, s[20:21]
	s_add_i32 s16, s4, 1216
	s_and_b32 s17, s16, 15
	s_lshr_b32 s18, s16, 4
	s_mul_i32 s17, s17, 1441792
	s_lshl_b32 s18, s18, 8
	s_add_u32 s17, s17, s18
	s_add_u32 s20, s8, s17
	s_addc_u32 s21, s9, 0
	global_load_dwordx4 v[90:93], v159, s[20:21]
	global_load_dwordx4 v[94:97], v160, s[20:21]
	s_barrier
	v_add_u32_e32 v149, 0x0, v147
	v_add_u32_e32 v150, 0x400, v147
	ds_read2_b32 v[98:99], v149 offset1:65
	ds_read2_b32 v[100:101], v149 offset0:130 offset1:195
	ds_read2_b32 v[102:103], v150 offset0:4 offset1:69
	ds_read2_b32 v[104:105], v150 offset0:134 offset1:199
	v_add_u32_e32 v151, 0x4100, v147
	v_add_u32_e32 v152, 0x4500, v147
	ds_read2_b32 v[106:107], v151 offset1:65
	ds_read2_b32 v[108:109], v151 offset0:130 offset1:195
	ds_read2_b32 v[110:111], v152 offset0:4 offset1:69
	ds_read2_b32 v[112:113], v152 offset0:134 offset1:199
	v_add_u32_e32 v153, 0x8200, v147
	v_add_u32_e32 v154, 0x8600, v147
	ds_read2_b32 v[114:115], v153 offset1:65
	ds_read2_b32 v[116:117], v153 offset0:130 offset1:195
	ds_read2_b32 v[118:119], v154 offset0:4 offset1:69
	ds_read2_b32 v[120:121], v154 offset0:134 offset1:199
	v_add_u32_e32 v155, 0xc300, v147
	v_add_u32_e32 v156, 0xc700, v147
	ds_read2_b32 v[122:123], v155 offset1:65
	ds_read2_b32 v[124:125], v155 offset0:130 offset1:195
	ds_read2_b32 v[126:127], v156 offset0:4 offset1:69
	ds_read2_b32 v[128:129], v156 offset0:134 offset1:199
	s_add_i32 s16, s4, 256
	s_and_b32 s17, s16, 15
	s_lshr_b32 s18, s16, 4
	s_sub_i32 s23, s18, 44
	s_cmp_lt_u32 s18, 44
	s_cselect_b32 s22, s18, s23
	s_cselect_b32 s23, 0, 0x80
	s_lshr_b32 s18, s22, 1
	s_lshl_b32 s18, s18, 8
	s_and_b32 s22, s22, 1
	s_lshl_b32 s22, s22, 6
	s_add_i32 s22, s22, s18
	s_add_i32 s22, s22, s23
	s_mul_i32 s22, s22, 2048
	s_lshl_b32 s17, s17, 7
	s_add_u32 s22, s22, s17
	s_add_u32 s20, s12, s22
	s_addc_u32 s21, s13, 0
	s_waitcnt lgkmcnt(12)
	v_cvt_pk_bf16_f32 v130, v98, v99
	v_cvt_pk_bf16_f32 v131, v100, v101
	v_cvt_pk_bf16_f32 v132, v102, v103
	v_cvt_pk_bf16_f32 v133, v104, v105
	global_store_dwordx4 v161, v[130:133], s[20:21] sc1
	s_add_i32 s16, s4, 320
	s_and_b32 s17, s16, 15
	s_lshr_b32 s18, s16, 4
	s_sub_i32 s23, s18, 44
	s_cmp_lt_u32 s18, 44
	s_cselect_b32 s22, s18, s23
	s_cselect_b32 s23, 0, 0x80
	s_lshr_b32 s18, s22, 1
	s_lshl_b32 s18, s18, 8
	s_and_b32 s22, s22, 1
	s_lshl_b32 s22, s22, 6
	s_add_i32 s22, s22, s18
	s_add_i32 s22, s22, s23
	s_mul_i32 s22, s22, 2048
	s_lshl_b32 s17, s17, 7
	s_add_u32 s22, s22, s17
	s_add_u32 s20, s12, s22
	s_addc_u32 s21, s13, 0
	s_waitcnt lgkmcnt(8)
	v_cvt_pk_bf16_f32 v134, v106, v107
	v_cvt_pk_bf16_f32 v135, v108, v109
	v_cvt_pk_bf16_f32 v136, v110, v111
	v_cvt_pk_bf16_f32 v137, v112, v113
	global_store_dwordx4 v161, v[134:137], s[20:21] sc1
	s_add_i32 s16, s4, 384
	s_and_b32 s17, s16, 15
	s_lshr_b32 s18, s16, 4
	s_sub_i32 s23, s18, 44
	s_cmp_lt_u32 s18, 44
	s_cselect_b32 s22, s18, s23
	s_cselect_b32 s23, 0, 0x80
	s_lshr_b32 s18, s22, 1
	s_lshl_b32 s18, s18, 8
	s_and_b32 s22, s22, 1
	s_lshl_b32 s22, s22, 6
	s_add_i32 s22, s22, s18
	s_add_i32 s22, s22, s23
	s_mul_i32 s22, s22, 2048
	s_lshl_b32 s17, s17, 7
	s_add_u32 s22, s22, s17
	s_add_u32 s20, s12, s22
	s_addc_u32 s21, s13, 0
	s_waitcnt lgkmcnt(4)
	v_cvt_pk_bf16_f32 v138, v114, v115
	v_cvt_pk_bf16_f32 v139, v116, v117
	v_cvt_pk_bf16_f32 v140, v118, v119
	v_cvt_pk_bf16_f32 v141, v120, v121
	global_store_dwordx4 v161, v[138:141], s[20:21] sc1
	s_add_i32 s16, s4, 448
	s_and_b32 s17, s16, 15
	s_lshr_b32 s18, s16, 4
	s_sub_i32 s23, s18, 44
	s_cmp_lt_u32 s18, 44
	s_cselect_b32 s22, s18, s23
	s_cselect_b32 s23, 0, 0x80
	s_lshr_b32 s18, s22, 1
	s_lshl_b32 s18, s18, 8
	s_and_b32 s22, s22, 1
	s_lshl_b32 s22, s22, 6
	s_add_i32 s22, s22, s18
	s_add_i32 s22, s22, s23
	s_mul_i32 s22, s22, 2048
	s_lshl_b32 s17, s17, 7
	s_add_u32 s22, s22, s17
	s_add_u32 s20, s12, s22
	s_addc_u32 s21, s13, 0
	s_waitcnt lgkmcnt(0)
	v_cvt_pk_bf16_f32 v142, v122, v123
	v_cvt_pk_bf16_f32 v143, v124, v125
	v_cvt_pk_bf16_f32 v144, v126, v127
	v_cvt_pk_bf16_f32 v145, v128, v129
	global_store_dwordx4 v161, v[142:145], s[20:21] sc1
	s_waitcnt vmcnt(28)
	v_add_u32_e32 v148, 0x10400, v146
	ds_write2_b32 v148, v2, v3 offset1:1
	ds_write2_b32 v148, v4, v5 offset0:2 offset1:3
	v_add_u32_e32 v148, 0x12480, v146
	ds_write2_b32 v148, v6, v7 offset1:1
	ds_write2_b32 v148, v8, v9 offset0:2 offset1:3
	v_add_u32_e32 v148, 0x14500, v146
	ds_write2_b32 v148, v10, v11 offset1:1
	ds_write2_b32 v148, v12, v13 offset0:2 offset1:3
	v_add_u32_e32 v148, 0x16580, v146
	ds_write2_b32 v148, v14, v15 offset1:1
	ds_write2_b32 v148, v16, v17 offset0:2 offset1:3
	v_add_u32_e32 v148, 0x18600, v146
	ds_write2_b32 v148, v18, v19 offset1:1
	ds_write2_b32 v148, v20, v21 offset0:2 offset1:3
	v_add_u32_e32 v148, 0x1a680, v146
	ds_write2_b32 v148, v22, v23 offset1:1
	ds_write2_b32 v148, v24, v25 offset0:2 offset1:3
	v_add_u32_e32 v148, 0x1c700, v146
	ds_write2_b32 v148, v26, v27 offset1:1
	ds_write2_b32 v148, v28, v29 offset0:2 offset1:3
	v_add_u32_e32 v148, 0x1e780, v146
	ds_write2_b32 v148, v30, v31 offset1:1
	ds_write2_b32 v148, v32, v33 offset0:2 offset1:3
	s_waitcnt lgkmcnt(0)
	s_add_i32 s16, s4, 1280
	s_and_b32 s17, s16, 15
	s_lshr_b32 s18, s16, 4
	s_mul_i32 s17, s17, 1441792
	s_lshl_b32 s18, s18, 8
	s_add_u32 s17, s17, s18
	s_add_u32 s20, s8, s17
	s_addc_u32 s21, s9, 0
	global_load_dwordx4 v[2:5], v159, s[20:21]
	global_load_dwordx4 v[6:9], v160, s[20:21]
	s_add_i32 s16, s4, 1344
	s_and_b32 s17, s16, 15
	s_lshr_b32 s18, s16, 4
	s_mul_i32 s17, s17, 1441792
	s_lshl_b32 s18, s18, 8
	s_add_u32 s17, s17, s18
	s_add_u32 s20, s8, s17
	s_addc_u32 s21, s9, 0
	global_load_dwordx4 v[10:13], v159, s[20:21]
	global_load_dwordx4 v[14:17], v160, s[20:21]
	s_barrier
	v_add_u32_e32 v149, 0x10400, v147
	v_add_u32_e32 v150, 0x10800, v147
	ds_read2_b32 v[98:99], v149 offset1:65
	ds_read2_b32 v[100:101], v149 offset0:130 offset1:195
	ds_read2_b32 v[102:103], v150 offset0:4 offset1:69
	ds_read2_b32 v[104:105], v150 offset0:134 offset1:199
	v_add_u32_e32 v151, 0x14500, v147
	v_add_u32_e32 v152, 0x14900, v147
	ds_read2_b32 v[106:107], v151 offset1:65
	ds_read2_b32 v[108:109], v151 offset0:130 offset1:195
	ds_read2_b32 v[110:111], v152 offset0:4 offset1:69
	ds_read2_b32 v[112:113], v152 offset0:134 offset1:199
	v_add_u32_e32 v153, 0x18600, v147
	v_add_u32_e32 v154, 0x18a00, v147
	ds_read2_b32 v[114:115], v153 offset1:65
	ds_read2_b32 v[116:117], v153 offset0:130 offset1:195
	ds_read2_b32 v[118:119], v154 offset0:4 offset1:69
	ds_read2_b32 v[120:121], v154 offset0:134 offset1:199
	v_add_u32_e32 v155, 0x1c700, v147
	v_add_u32_e32 v156, 0x1cb00, v147
	ds_read2_b32 v[122:123], v155 offset1:65
	ds_read2_b32 v[124:125], v155 offset0:130 offset1:195
	ds_read2_b32 v[126:127], v156 offset0:4 offset1:69
	ds_read2_b32 v[128:129], v156 offset0:134 offset1:199
	s_add_i32 s16, s4, 512
	s_and_b32 s17, s16, 15
	s_lshr_b32 s18, s16, 4
	s_sub_i32 s23, s18, 44
	s_cmp_lt_u32 s18, 44
	s_cselect_b32 s22, s18, s23
	s_cselect_b32 s23, 0, 0x80
	s_lshr_b32 s18, s22, 1
	s_lshl_b32 s18, s18, 8
	s_and_b32 s22, s22, 1
	s_lshl_b32 s22, s22, 6
	s_add_i32 s22, s22, s18
	s_add_i32 s22, s22, s23
	s_mul_i32 s22, s22, 2048
	s_lshl_b32 s17, s17, 7
	s_add_u32 s22, s22, s17
	s_add_u32 s20, s12, s22
	s_addc_u32 s21, s13, 0
	s_waitcnt lgkmcnt(12)
	v_cvt_pk_bf16_f32 v130, v98, v99
	v_cvt_pk_bf16_f32 v131, v100, v101
	v_cvt_pk_bf16_f32 v132, v102, v103
	v_cvt_pk_bf16_f32 v133, v104, v105
	global_store_dwordx4 v161, v[130:133], s[20:21] sc1
	s_add_i32 s16, s4, 576
	s_and_b32 s17, s16, 15
	s_lshr_b32 s18, s16, 4
	s_sub_i32 s23, s18, 44
	s_cmp_lt_u32 s18, 44
	s_cselect_b32 s22, s18, s23
	s_cselect_b32 s23, 0, 0x80
	s_lshr_b32 s18, s22, 1
	s_lshl_b32 s18, s18, 8
	s_and_b32 s22, s22, 1
	s_lshl_b32 s22, s22, 6
	s_add_i32 s22, s22, s18
	s_add_i32 s22, s22, s23
	s_mul_i32 s22, s22, 2048
	s_lshl_b32 s17, s17, 7
	s_add_u32 s22, s22, s17
	s_add_u32 s20, s12, s22
	s_addc_u32 s21, s13, 0
	s_waitcnt lgkmcnt(8)
	v_cvt_pk_bf16_f32 v134, v106, v107
	v_cvt_pk_bf16_f32 v135, v108, v109
	v_cvt_pk_bf16_f32 v136, v110, v111
	v_cvt_pk_bf16_f32 v137, v112, v113
	global_store_dwordx4 v161, v[134:137], s[20:21] sc1
	s_add_i32 s16, s4, 640
	s_and_b32 s17, s16, 15
	s_lshr_b32 s18, s16, 4
	s_sub_i32 s23, s18, 44
	s_cmp_lt_u32 s18, 44
	s_cselect_b32 s22, s18, s23
	s_cselect_b32 s23, 0, 0x80
	s_lshr_b32 s18, s22, 1
	s_lshl_b32 s18, s18, 8
	s_and_b32 s22, s22, 1
	s_lshl_b32 s22, s22, 6
	s_add_i32 s22, s22, s18
	s_add_i32 s22, s22, s23
	s_mul_i32 s22, s22, 2048
	s_lshl_b32 s17, s17, 7
	s_add_u32 s22, s22, s17
	s_add_u32 s20, s12, s22
	s_addc_u32 s21, s13, 0
	s_waitcnt lgkmcnt(4)
	v_cvt_pk_bf16_f32 v138, v114, v115
	v_cvt_pk_bf16_f32 v139, v116, v117
	v_cvt_pk_bf16_f32 v140, v118, v119
	v_cvt_pk_bf16_f32 v141, v120, v121
	global_store_dwordx4 v161, v[138:141], s[20:21] sc1
	s_add_i32 s16, s4, 704
	s_and_b32 s17, s16, 15
	s_lshr_b32 s18, s16, 4
	s_sub_i32 s23, s18, 44
	s_cmp_lt_u32 s18, 44
	s_cselect_b32 s22, s18, s23
	s_cselect_b32 s23, 0, 0x80
	s_lshr_b32 s18, s22, 1
	s_lshl_b32 s18, s18, 8
	s_and_b32 s22, s22, 1
	s_lshl_b32 s22, s22, 6
	s_add_i32 s22, s22, s18
	s_add_i32 s22, s22, s23
	s_mul_i32 s22, s22, 2048
	s_lshl_b32 s17, s17, 7
	s_add_u32 s22, s22, s17
	s_add_u32 s20, s12, s22
	s_addc_u32 s21, s13, 0
	s_waitcnt lgkmcnt(0)
	v_cvt_pk_bf16_f32 v142, v122, v123
	v_cvt_pk_bf16_f32 v143, v124, v125
	v_cvt_pk_bf16_f32 v144, v126, v127
	v_cvt_pk_bf16_f32 v145, v128, v129
	global_store_dwordx4 v161, v[142:145], s[20:21] sc1
	s_waitcnt vmcnt(24)
	v_add_u32_e32 v148, 0x0, v146
	ds_write2_b32 v148, v34, v35 offset1:1
	ds_write2_b32 v148, v36, v37 offset0:2 offset1:3
	v_add_u32_e32 v148, 0x2080, v146
	ds_write2_b32 v148, v38, v39 offset1:1
	ds_write2_b32 v148, v40, v41 offset0:2 offset1:3
	v_add_u32_e32 v148, 0x4100, v146
	ds_write2_b32 v148, v42, v43 offset1:1
	ds_write2_b32 v148, v44, v45 offset0:2 offset1:3
	v_add_u32_e32 v148, 0x6180, v146
	ds_write2_b32 v148, v46, v47 offset1:1
	ds_write2_b32 v148, v48, v49 offset0:2 offset1:3
	v_add_u32_e32 v148, 0x8200, v146
	ds_write2_b32 v148, v50, v51 offset1:1
	ds_write2_b32 v148, v52, v53 offset0:2 offset1:3
	v_add_u32_e32 v148, 0xa280, v146
	ds_write2_b32 v148, v54, v55 offset1:1
	ds_write2_b32 v148, v56, v57 offset0:2 offset1:3
	v_add_u32_e32 v148, 0xc300, v146
	ds_write2_b32 v148, v58, v59 offset1:1
	ds_write2_b32 v148, v60, v61 offset0:2 offset1:3
	v_add_u32_e32 v148, 0xe380, v146
	ds_write2_b32 v148, v62, v63 offset1:1
	ds_write2_b32 v148, v64, v65 offset0:2 offset1:3
	s_waitcnt lgkmcnt(0)
	s_barrier
	v_add_u32_e32 v149, 0x0, v147
	v_add_u32_e32 v150, 0x400, v147
	ds_read2_b32 v[98:99], v149 offset1:65
	ds_read2_b32 v[100:101], v149 offset0:130 offset1:195
	ds_read2_b32 v[102:103], v150 offset0:4 offset1:69
	ds_read2_b32 v[104:105], v150 offset0:134 offset1:199
	v_add_u32_e32 v151, 0x4100, v147
	v_add_u32_e32 v152, 0x4500, v147
	ds_read2_b32 v[106:107], v151 offset1:65
	ds_read2_b32 v[108:109], v151 offset0:130 offset1:195
	ds_read2_b32 v[110:111], v152 offset0:4 offset1:69
	ds_read2_b32 v[112:113], v152 offset0:134 offset1:199
	v_add_u32_e32 v153, 0x8200, v147
	v_add_u32_e32 v154, 0x8600, v147
	ds_read2_b32 v[114:115], v153 offset1:65
	ds_read2_b32 v[116:117], v153 offset0:130 offset1:195
	ds_read2_b32 v[118:119], v154 offset0:4 offset1:69
	ds_read2_b32 v[120:121], v154 offset0:134 offset1:199
	v_add_u32_e32 v155, 0xc300, v147
	v_add_u32_e32 v156, 0xc700, v147
	ds_read2_b32 v[122:123], v155 offset1:65
	ds_read2_b32 v[124:125], v155 offset0:130 offset1:195
	ds_read2_b32 v[126:127], v156 offset0:4 offset1:69
	ds_read2_b32 v[128:129], v156 offset0:134 offset1:199
	s_add_i32 s16, s4, 768
	s_and_b32 s17, s16, 15
	s_lshr_b32 s18, s16, 4
	s_sub_i32 s23, s18, 44
	s_cmp_lt_u32 s18, 44
	s_cselect_b32 s22, s18, s23
	s_cselect_b32 s23, 0, 0x80
	s_lshr_b32 s18, s22, 1
	s_lshl_b32 s18, s18, 8
	s_and_b32 s22, s22, 1
	s_lshl_b32 s22, s22, 6
	s_add_i32 s22, s22, s18
	s_add_i32 s22, s22, s23
	s_mul_i32 s22, s22, 2048
	s_lshl_b32 s17, s17, 7
	s_add_u32 s22, s22, s17
	s_add_u32 s20, s12, s22
	s_addc_u32 s21, s13, 0
	s_waitcnt lgkmcnt(12)
	v_cvt_pk_bf16_f32 v130, v98, v99
	v_cvt_pk_bf16_f32 v131, v100, v101
	v_cvt_pk_bf16_f32 v132, v102, v103
	v_cvt_pk_bf16_f32 v133, v104, v105
	global_store_dwordx4 v161, v[130:133], s[20:21] sc1
	s_add_i32 s16, s4, 832
	s_and_b32 s17, s16, 15
	s_lshr_b32 s18, s16, 4
	s_sub_i32 s23, s18, 44
	s_cmp_lt_u32 s18, 44
	s_cselect_b32 s22, s18, s23
	s_cselect_b32 s23, 0, 0x80
	s_lshr_b32 s18, s22, 1
	s_lshl_b32 s18, s18, 8
	s_and_b32 s22, s22, 1
	s_lshl_b32 s22, s22, 6
	s_add_i32 s22, s22, s18
	s_add_i32 s22, s22, s23
	s_mul_i32 s22, s22, 2048
	s_lshl_b32 s17, s17, 7
	s_add_u32 s22, s22, s17
	s_add_u32 s20, s12, s22
	s_addc_u32 s21, s13, 0
	s_waitcnt lgkmcnt(8)
	v_cvt_pk_bf16_f32 v134, v106, v107
	v_cvt_pk_bf16_f32 v135, v108, v109
	v_cvt_pk_bf16_f32 v136, v110, v111
	v_cvt_pk_bf16_f32 v137, v112, v113
	global_store_dwordx4 v161, v[134:137], s[20:21] sc1
	s_add_i32 s16, s4, 896
	s_and_b32 s17, s16, 15
	s_lshr_b32 s18, s16, 4
	s_sub_i32 s23, s18, 44
	s_cmp_lt_u32 s18, 44
	s_cselect_b32 s22, s18, s23
	s_cselect_b32 s23, 0, 0x80
	s_lshr_b32 s18, s22, 1
	s_lshl_b32 s18, s18, 8
	s_and_b32 s22, s22, 1
	s_lshl_b32 s22, s22, 6
	s_add_i32 s22, s22, s18
	s_add_i32 s22, s22, s23
	s_mul_i32 s22, s22, 2048
	s_lshl_b32 s17, s17, 7
	s_add_u32 s22, s22, s17
	s_add_u32 s20, s12, s22
	s_addc_u32 s21, s13, 0
	s_waitcnt lgkmcnt(4)
	v_cvt_pk_bf16_f32 v138, v114, v115
	v_cvt_pk_bf16_f32 v139, v116, v117
	v_cvt_pk_bf16_f32 v140, v118, v119
	v_cvt_pk_bf16_f32 v141, v120, v121
	global_store_dwordx4 v161, v[138:141], s[20:21] sc1
	s_add_i32 s16, s4, 960
	s_and_b32 s17, s16, 15
	s_lshr_b32 s18, s16, 4
	s_sub_i32 s23, s18, 44
	s_cmp_lt_u32 s18, 44
	s_cselect_b32 s22, s18, s23
	s_cselect_b32 s23, 0, 0x80
	s_lshr_b32 s18, s22, 1
	s_lshl_b32 s18, s18, 8
	s_and_b32 s22, s22, 1
	s_lshl_b32 s22, s22, 6
	s_add_i32 s22, s22, s18
	s_add_i32 s22, s22, s23
	s_mul_i32 s22, s22, 2048
	s_lshl_b32 s17, s17, 7
	s_add_u32 s22, s22, s17
	s_add_u32 s20, s12, s22
	s_addc_u32 s21, s13, 0
	s_waitcnt lgkmcnt(0)
	v_cvt_pk_bf16_f32 v142, v122, v123
	v_cvt_pk_bf16_f32 v143, v124, v125
	v_cvt_pk_bf16_f32 v144, v126, v127
	v_cvt_pk_bf16_f32 v145, v128, v129
	global_store_dwordx4 v161, v[142:145], s[20:21] sc1
	s_waitcnt vmcnt(16)
	v_add_u32_e32 v148, 0x10400, v146
	ds_write2_b32 v148, v66, v67 offset1:1
	ds_write2_b32 v148, v68, v69 offset0:2 offset1:3
	v_add_u32_e32 v148, 0x12480, v146
	ds_write2_b32 v148, v70, v71 offset1:1
	ds_write2_b32 v148, v72, v73 offset0:2 offset1:3
	v_add_u32_e32 v148, 0x14500, v146
	ds_write2_b32 v148, v74, v75 offset1:1
	ds_write2_b32 v148, v76, v77 offset0:2 offset1:3
	v_add_u32_e32 v148, 0x16580, v146
	ds_write2_b32 v148, v78, v79 offset1:1
	ds_write2_b32 v148, v80, v81 offset0:2 offset1:3
	v_add_u32_e32 v148, 0x18600, v146
	ds_write2_b32 v148, v82, v83 offset1:1
	ds_write2_b32 v148, v84, v85 offset0:2 offset1:3
	v_add_u32_e32 v148, 0x1a680, v146
	ds_write2_b32 v148, v86, v87 offset1:1
	ds_write2_b32 v148, v88, v89 offset0:2 offset1:3
	v_add_u32_e32 v148, 0x1c700, v146
	ds_write2_b32 v148, v90, v91 offset1:1
	ds_write2_b32 v148, v92, v93 offset0:2 offset1:3
	v_add_u32_e32 v148, 0x1e780, v146
	ds_write2_b32 v148, v94, v95 offset1:1
	ds_write2_b32 v148, v96, v97 offset0:2 offset1:3
	s_waitcnt lgkmcnt(0)
	s_barrier
	v_add_u32_e32 v149, 0x10400, v147
	v_add_u32_e32 v150, 0x10800, v147
	ds_read2_b32 v[98:99], v149 offset1:65
	ds_read2_b32 v[100:101], v149 offset0:130 offset1:195
	ds_read2_b32 v[102:103], v150 offset0:4 offset1:69
	ds_read2_b32 v[104:105], v150 offset0:134 offset1:199
	v_add_u32_e32 v151, 0x14500, v147
	v_add_u32_e32 v152, 0x14900, v147
	ds_read2_b32 v[106:107], v151 offset1:65
	ds_read2_b32 v[108:109], v151 offset0:130 offset1:195
	ds_read2_b32 v[110:111], v152 offset0:4 offset1:69
	ds_read2_b32 v[112:113], v152 offset0:134 offset1:199
	v_add_u32_e32 v153, 0x18600, v147
	v_add_u32_e32 v154, 0x18a00, v147
	ds_read2_b32 v[114:115], v153 offset1:65
	ds_read2_b32 v[116:117], v153 offset0:130 offset1:195
	ds_read2_b32 v[118:119], v154 offset0:4 offset1:69
	ds_read2_b32 v[120:121], v154 offset0:134 offset1:199
	v_add_u32_e32 v155, 0x1c700, v147
	v_add_u32_e32 v156, 0x1cb00, v147
	ds_read2_b32 v[122:123], v155 offset1:65
	ds_read2_b32 v[124:125], v155 offset0:130 offset1:195
	ds_read2_b32 v[126:127], v156 offset0:4 offset1:69
	ds_read2_b32 v[128:129], v156 offset0:134 offset1:199
	s_add_i32 s16, s4, 1024
	s_and_b32 s17, s16, 15
	s_lshr_b32 s18, s16, 4
	s_sub_i32 s23, s18, 44
	s_cmp_lt_u32 s18, 44
	s_cselect_b32 s22, s18, s23
	s_cselect_b32 s23, 0, 0x80
	s_lshr_b32 s18, s22, 1
	s_lshl_b32 s18, s18, 8
	s_and_b32 s22, s22, 1
	s_lshl_b32 s22, s22, 6
	s_add_i32 s22, s22, s18
	s_add_i32 s22, s22, s23
	s_mul_i32 s22, s22, 2048
	s_lshl_b32 s17, s17, 7
	s_add_u32 s22, s22, s17
	s_add_u32 s20, s12, s22
	s_addc_u32 s21, s13, 0
	s_waitcnt lgkmcnt(12)
	v_cvt_pk_bf16_f32 v130, v98, v99
	v_cvt_pk_bf16_f32 v131, v100, v101
	v_cvt_pk_bf16_f32 v132, v102, v103
	v_cvt_pk_bf16_f32 v133, v104, v105
	global_store_dwordx4 v161, v[130:133], s[20:21] sc1
	s_add_i32 s16, s4, 1088
	s_and_b32 s17, s16, 15
	s_lshr_b32 s18, s16, 4
	s_sub_i32 s23, s18, 44
	s_cmp_lt_u32 s18, 44
	s_cselect_b32 s22, s18, s23
	s_cselect_b32 s23, 0, 0x80
	s_lshr_b32 s18, s22, 1
	s_lshl_b32 s18, s18, 8
	s_and_b32 s22, s22, 1
	s_lshl_b32 s22, s22, 6
	s_add_i32 s22, s22, s18
	s_add_i32 s22, s22, s23
	s_mul_i32 s22, s22, 2048
	s_lshl_b32 s17, s17, 7
	s_add_u32 s22, s22, s17
	s_add_u32 s20, s12, s22
	s_addc_u32 s21, s13, 0
	s_waitcnt lgkmcnt(8)
	v_cvt_pk_bf16_f32 v134, v106, v107
	v_cvt_pk_bf16_f32 v135, v108, v109
	v_cvt_pk_bf16_f32 v136, v110, v111
	v_cvt_pk_bf16_f32 v137, v112, v113
	global_store_dwordx4 v161, v[134:137], s[20:21] sc1
	s_add_i32 s16, s4, 1152
	s_and_b32 s17, s16, 15
	s_lshr_b32 s18, s16, 4
	s_sub_i32 s23, s18, 44
	s_cmp_lt_u32 s18, 44
	s_cselect_b32 s22, s18, s23
	s_cselect_b32 s23, 0, 0x80
	s_lshr_b32 s18, s22, 1
	s_lshl_b32 s18, s18, 8
	s_and_b32 s22, s22, 1
	s_lshl_b32 s22, s22, 6
	s_add_i32 s22, s22, s18
	s_add_i32 s22, s22, s23
	s_mul_i32 s22, s22, 2048
	s_lshl_b32 s17, s17, 7
	s_add_u32 s22, s22, s17
	s_add_u32 s20, s12, s22
	s_addc_u32 s21, s13, 0
	s_waitcnt lgkmcnt(4)
	v_cvt_pk_bf16_f32 v138, v114, v115
	v_cvt_pk_bf16_f32 v139, v116, v117
	v_cvt_pk_bf16_f32 v140, v118, v119
	v_cvt_pk_bf16_f32 v141, v120, v121
	global_store_dwordx4 v161, v[138:141], s[20:21] sc1
	s_add_i32 s16, s4, 1216
	s_and_b32 s17, s16, 15
	s_lshr_b32 s18, s16, 4
	s_sub_i32 s23, s18, 44
	s_cmp_lt_u32 s18, 44
	s_cselect_b32 s22, s18, s23
	s_cselect_b32 s23, 0, 0x80
	s_lshr_b32 s18, s22, 1
	s_lshl_b32 s18, s18, 8
	s_and_b32 s22, s22, 1
	s_lshl_b32 s22, s22, 6
	s_add_i32 s22, s22, s18
	s_add_i32 s22, s22, s23
	s_mul_i32 s22, s22, 2048
	s_lshl_b32 s17, s17, 7
	s_add_u32 s22, s22, s17
	s_add_u32 s20, s12, s22
	s_addc_u32 s21, s13, 0
	s_waitcnt lgkmcnt(0)
	v_cvt_pk_bf16_f32 v142, v122, v123
	v_cvt_pk_bf16_f32 v143, v124, v125
	v_cvt_pk_bf16_f32 v144, v126, v127
	v_cvt_pk_bf16_f32 v145, v128, v129
	global_store_dwordx4 v161, v[142:145], s[20:21] sc1
	s_waitcnt vmcnt(12)
	v_add_u32_e32 v148, 0x0, v146
	ds_write2_b32 v148, v2, v3 offset1:1
	ds_write2_b32 v148, v4, v5 offset0:2 offset1:3
	v_add_u32_e32 v148, 0x2080, v146
	ds_write2_b32 v148, v6, v7 offset1:1
	ds_write2_b32 v148, v8, v9 offset0:2 offset1:3
	v_add_u32_e32 v148, 0x4100, v146
	ds_write2_b32 v148, v10, v11 offset1:1
	ds_write2_b32 v148, v12, v13 offset0:2 offset1:3
	v_add_u32_e32 v148, 0x6180, v146
	ds_write2_b32 v148, v14, v15 offset1:1
	ds_write2_b32 v148, v16, v17 offset0:2 offset1:3
	s_waitcnt lgkmcnt(0)
	s_barrier
	v_add_u32_e32 v149, 0x0, v147
	v_add_u32_e32 v150, 0x400, v147
	ds_read2_b32 v[98:99], v149 offset1:65
	ds_read2_b32 v[100:101], v149 offset0:130 offset1:195
	ds_read2_b32 v[102:103], v150 offset0:4 offset1:69
	ds_read2_b32 v[104:105], v150 offset0:134 offset1:199
	v_add_u32_e32 v151, 0x4100, v147
	v_add_u32_e32 v152, 0x4500, v147
	ds_read2_b32 v[106:107], v151 offset1:65
	ds_read2_b32 v[108:109], v151 offset0:130 offset1:195
	ds_read2_b32 v[110:111], v152 offset0:4 offset1:69
	ds_read2_b32 v[112:113], v152 offset0:134 offset1:199
	s_add_i32 s16, s4, 1280
	s_and_b32 s17, s16, 15
	s_lshr_b32 s18, s16, 4
	s_sub_i32 s23, s18, 44
	s_cmp_lt_u32 s18, 44
	s_cselect_b32 s22, s18, s23
	s_cselect_b32 s23, 0, 0x80
	s_lshr_b32 s18, s22, 1
	s_lshl_b32 s18, s18, 8
	s_and_b32 s22, s22, 1
	s_lshl_b32 s22, s22, 6
	s_add_i32 s22, s22, s18
	s_add_i32 s22, s22, s23
	s_mul_i32 s22, s22, 2048
	s_lshl_b32 s17, s17, 7
	s_add_u32 s22, s22, s17
	s_add_u32 s20, s12, s22
	s_addc_u32 s21, s13, 0
	s_waitcnt lgkmcnt(4)
	v_cvt_pk_bf16_f32 v130, v98, v99
	v_cvt_pk_bf16_f32 v131, v100, v101
	v_cvt_pk_bf16_f32 v132, v102, v103
	v_cvt_pk_bf16_f32 v133, v104, v105
	global_store_dwordx4 v161, v[130:133], s[20:21] sc1
	s_add_i32 s16, s4, 1344
	s_and_b32 s17, s16, 15
	s_lshr_b32 s18, s16, 4
	s_sub_i32 s23, s18, 44
	s_cmp_lt_u32 s18, 44
	s_cselect_b32 s22, s18, s23
	s_cselect_b32 s23, 0, 0x80
	s_lshr_b32 s18, s22, 1
	s_lshl_b32 s18, s18, 8
	s_and_b32 s22, s22, 1
	s_lshl_b32 s22, s22, 6
	s_add_i32 s22, s22, s18
	s_add_i32 s22, s22, s23
	s_mul_i32 s22, s22, 2048
	s_lshl_b32 s17, s17, 7
	s_add_u32 s22, s22, s17
	s_add_u32 s20, s12, s22
	s_addc_u32 s21, s13, 0
	s_waitcnt lgkmcnt(0)
	v_cvt_pk_bf16_f32 v134, v106, v107
	v_cvt_pk_bf16_f32 v135, v108, v109
	v_cvt_pk_bf16_f32 v136, v110, v111
	v_cvt_pk_bf16_f32 v137, v112, v113
	global_store_dwordx4 v161, v[134:137], s[20:21] sc1
